# v71 + nt (streaming) hint on the scan A / scan B loads of group B
# speedup vs baseline: 1.0033x; 1.0033x over previous
.LBB0_1053:
	v_add_co_u32_e32 v12, vcc, 0xfdff1000, v6
	s_nop 1
	v_addc_co_u32_e32 v13, vcc, -1, v7, vcc
	global_load_dwordx2 v[68:69], v[12:13], off nt
	v_add_co_u32_e32 v12, vcc, 0xffff1000, v6
	s_nop 1
	v_addc_co_u32_e32 v13, vcc, -1, v7, vcc
	global_load_dwordx2 v[74:75], v[12:13], off nt
	v_add_co_u32_e32 v12, vcc, 0xfdff2000, v6
	s_nop 1
	v_addc_co_u32_e32 v13, vcc, -1, v7, vcc
	global_load_dwordx2 v[60:61], v[12:13], off nt
	v_add_co_u32_e32 v12, vcc, 0xffff2000, v6
	s_nop 1
	v_addc_co_u32_e32 v13, vcc, -1, v7, vcc
	global_load_dwordx2 v[44:45], v[12:13], off nt
	v_add_co_u32_e32 v12, vcc, 0xfdff3000, v6
	s_nop 1
	v_addc_co_u32_e32 v13, vcc, -1, v7, vcc
	global_load_dwordx2 v[64:65], v[12:13], off nt
	v_add_co_u32_e32 v12, vcc, 0xffff3000, v6
	s_nop 1
	v_addc_co_u32_e32 v13, vcc, -1, v7, vcc
	global_load_dwordx2 v[46:47], v[12:13], off nt
	v_add_co_u32_e32 v12, vcc, 0xfdff4000, v6
	s_nop 1
	v_addc_co_u32_e32 v13, vcc, -1, v7, vcc
	global_load_dwordx2 v[62:63], v[12:13], off nt
	v_add_co_u32_e32 v12, vcc, 0xffff4000, v6
	s_nop 1
	v_addc_co_u32_e32 v13, vcc, -1, v7, vcc
	global_load_dwordx2 v[54:55], v[12:13], off nt
	v_add_co_u32_e32 v12, vcc, 0xfdff5000, v6
	s_nop 1
	v_addc_co_u32_e32 v13, vcc, -1, v7, vcc
	global_load_dwordx2 v[66:67], v[12:13], off nt
	v_add_co_u32_e32 v12, vcc, 0xffff5000, v6
	s_nop 1
	v_addc_co_u32_e32 v13, vcc, -1, v7, vcc
	global_load_dwordx2 v[58:59], v[12:13], off nt
	v_add_co_u32_e32 v12, vcc, 0xfdff6000, v6
	s_nop 1
	v_addc_co_u32_e32 v13, vcc, -1, v7, vcc
	global_load_dwordx2 v[50:51], v[12:13], off nt
	v_add_co_u32_e32 v12, vcc, 0xffff6000, v6
	s_nop 1
	v_addc_co_u32_e32 v13, vcc, -1, v7, vcc
	global_load_dwordx2 v[56:57], v[12:13], off nt
	v_add_co_u32_e32 v12, vcc, 0xfdff7000, v6
	s_nop 1
	v_addc_co_u32_e32 v13, vcc, -1, v7, vcc
	global_load_dwordx2 v[48:49], v[12:13], off nt
	v_add_co_u32_e32 v12, vcc, 0xffff7000, v6
	s_nop 1
	v_addc_co_u32_e32 v13, vcc, -1, v7, vcc
	global_load_dwordx2 v[18:19], v[12:13], off nt
	v_add_co_u32_e32 v12, vcc, 0xfdff8000, v6
	s_nop 1
	v_addc_co_u32_e32 v13, vcc, -1, v7, vcc
	global_load_dwordx2 v[52:53], v[12:13], off nt
	v_add_co_u32_e32 v12, vcc, 0xffff8000, v6
	s_nop 1
	v_addc_co_u32_e32 v13, vcc, -1, v7, vcc
	global_load_dwordx2 v[22:23], v[12:13], off nt
	v_add_co_u32_e32 v12, vcc, 0xfdff9000, v6
	s_nop 1
	v_addc_co_u32_e32 v13, vcc, -1, v7, vcc
	global_load_dwordx2 v[40:41], v[12:13], off nt
	v_add_co_u32_e32 v12, vcc, 0xffff9000, v6
	s_nop 1
	v_addc_co_u32_e32 v13, vcc, -1, v7, vcc
	global_load_dwordx2 v[24:25], v[12:13], off nt
	v_add_co_u32_e32 v12, vcc, 0xfdffa000, v6
	s_nop 1
	v_addc_co_u32_e32 v13, vcc, -1, v7, vcc
	global_load_dwordx2 v[38:39], v[12:13], off nt
	v_add_co_u32_e32 v12, vcc, 0xffffa000, v6
	s_nop 1
	v_addc_co_u32_e32 v13, vcc, -1, v7, vcc
	global_load_dwordx2 v[28:29], v[12:13], off nt
	v_add_co_u32_e32 v12, vcc, 0xfdffb000, v6
	s_nop 1
	v_addc_co_u32_e32 v13, vcc, -1, v7, vcc
	global_load_dwordx2 v[42:43], v[12:13], off nt
	v_add_co_u32_e32 v12, vcc, 0xffffb000, v6
	s_nop 1
	v_addc_co_u32_e32 v13, vcc, -1, v7, vcc
	global_load_dwordx2 v[70:71], v[12:13], off nt
	v_add_co_u32_e32 v12, vcc, 0xfdffc000, v6
	s_nop 1
	v_addc_co_u32_e32 v13, vcc, -1, v7, vcc
	global_load_dwordx2 v[30:31], v[12:13], off nt
	v_add_co_u32_e32 v12, vcc, 0xffffc000, v6
	s_nop 1
	v_addc_co_u32_e32 v13, vcc, -1, v7, vcc
	global_load_dwordx2 v[72:73], v[12:13], off nt
	v_add_co_u32_e32 v12, vcc, 0xfdffd000, v6
	s_nop 1
	v_addc_co_u32_e32 v13, vcc, -1, v7, vcc
	global_load_dwordx2 v[34:35], v[12:13], off nt
	v_add_co_u32_e32 v12, vcc, 0xffffd000, v6
	s_nop 1
	v_addc_co_u32_e32 v13, vcc, -1, v7, vcc
	v_add_co_u32_e32 v14, vcc, 0xfdffe000, v6
	global_load_dwordx2 v[12:13], v[12:13], off nt
	s_nop 0
	v_addc_co_u32_e32 v15, vcc, -1, v7, vcc
	global_load_dwordx2 v[32:33], v[14:15], off nt
	v_add_co_u32_e32 v14, vcc, 0xffffe000, v6
	s_nop 1
	v_addc_co_u32_e32 v15, vcc, -1, v7, vcc
	global_load_dwordx2 v[16:17], v[14:15], off nt
	v_add_co_u32_e32 v14, vcc, 0xfdfff000, v6
	s_nop 1
	v_addc_co_u32_e32 v15, vcc, -1, v7, vcc
	v_add_co_u32_e32 v20, vcc, 0xfe000000, v6
	global_load_dwordx2 v[36:37], v[14:15], off nt
	s_nop 0
	global_load_dwordx2 v[14:15], v[6:7], off offset:-4096 nt
	v_addc_co_u32_e32 v21, vcc, -1, v7, vcc
	global_load_dwordx2 v[26:27], v[20:21], off nt
	s_nop 0
	global_load_dwordx2 v[20:21], v[6:7], off nt
	s_waitcnt vmcnt(31)
	v_and_b32_e32 v82, 0xffff0000, v68
	v_lshlrev_b32_e32 v83, 16, v68
	v_mul_f32_e32 v68, 0x3fb8aa3b, v83
	v_pk_add_f32 v[8:9], v[8:9], v[82:83]
	s_waitcnt vmcnt(29)
	v_lshlrev_b32_e32 v83, 16, v60
	v_exp_f32_e32 v84, v68
	v_mul_f32_e32 v68, 0x3fb8aa3b, v82
	v_and_b32_e32 v82, 0xffff0000, v60
	v_mul_f32_e32 v60, 0x3fb8aa3b, v83
	v_exp_f32_e32 v86, v60
	v_pk_add_f32 v[8:9], v[8:9], v[82:83]
	v_mul_f32_e32 v60, 0x3fb8aa3b, v82
	s_waitcnt vmcnt(27)
	v_lshlrev_b32_e32 v83, 16, v64
	v_exp_f32_e32 v87, v60
	v_and_b32_e32 v82, 0xffff0000, v64
	v_mul_f32_e32 v60, 0x3fb8aa3b, v83
	v_exp_f32_e32 v88, v60
	v_pk_add_f32 v[8:9], v[8:9], v[82:83]
	v_mul_f32_e32 v60, 0x3fb8aa3b, v82
	s_waitcnt vmcnt(25)
	v_lshlrev_b32_e32 v83, 16, v62
	v_exp_f32_e32 v85, v68
	v_exp_f32_e32 v89, v60
	v_and_b32_e32 v82, 0xffff0000, v62
	v_mul_f32_e32 v60, 0x3fb8aa3b, v83
	v_exp_f32_e32 v90, v60
	v_pk_add_f32 v[8:9], v[8:9], v[82:83]
	v_mul_f32_e32 v60, 0x3fb8aa3b, v82
	s_waitcnt vmcnt(23)
	v_lshlrev_b32_e32 v83, 16, v66
	v_exp_f32_e32 v91, v60
	v_and_b32_e32 v82, 0xffff0000, v66
	v_mul_f32_e32 v60, 0x3fb8aa3b, v83
	v_and_b32_e32 v68, 0xffff0000, v69
	v_lshlrev_b32_e32 v69, 16, v69
	v_lshlrev_b32_e32 v80, 16, v74
	v_and_b32_e32 v81, 0xffff0000, v74
	v_exp_f32_e32 v92, v60
	v_pk_add_f32 v[8:9], v[8:9], v[82:83]
	v_mul_f32_e32 v60, 0x3fb8aa3b, v82
	v_lshlrev_b32_e32 v82, 16, v44
	v_and_b32_e32 v83, 0xffff0000, v44
	v_mul_f32_e32 v44, 0x3fb8aa3b, v69
	v_exp_f32_e32 v93, v60
	v_pk_fma_f32 v[2:3], v[2:3], v[84:85], v[80:81]
	v_exp_f32_e32 v80, v44
	v_mul_f32_e32 v44, 0x3fb8aa3b, v68
	v_and_b32_e32 v60, 0xffff0000, v61
	v_lshlrev_b32_e32 v61, 16, v61
	v_pk_add_f32 v[10:11], v[10:11], v[68:69]
	v_exp_f32_e32 v81, v44
	v_mul_f32_e32 v44, 0x3fb8aa3b, v61
	v_exp_f32_e32 v68, v44
	v_pk_add_f32 v[10:11], v[10:11], v[60:61]
	v_mul_f32_e32 v44, 0x3fb8aa3b, v60
	v_lshlrev_b32_e32 v61, 16, v65
	v_exp_f32_e32 v69, v44
	v_and_b32_e32 v60, 0xffff0000, v65
	v_mul_f32_e32 v44, 0x3fb8aa3b, v61
	v_exp_f32_e32 v64, v44
	v_pk_add_f32 v[10:11], v[10:11], v[60:61]
	v_mul_f32_e32 v44, 0x3fb8aa3b, v60
	v_lshlrev_b32_e32 v61, 16, v63
	v_exp_f32_e32 v65, v44
	v_and_b32_e32 v60, 0xffff0000, v63
	v_mul_f32_e32 v44, 0x3fb8aa3b, v61
	v_exp_f32_e32 v62, v44
	v_pk_add_f32 v[10:11], v[10:11], v[60:61]
	v_mul_f32_e32 v44, 0x3fb8aa3b, v60
	v_and_b32_e32 v66, 0xffff0000, v67
	v_lshlrev_b32_e32 v67, 16, v67
	v_lshlrev_b32_e32 v74, 16, v75
	v_and_b32_e32 v75, 0xffff0000, v75
	v_exp_f32_e32 v63, v44
	v_mul_f32_e32 v44, 0x3fb8aa3b, v67
	v_pk_add_f32 v[60:61], v[10:11], v[66:67]
	v_mul_f32_e32 v10, 0x3fb8aa3b, v66
	v_pk_fma_f32 v[2:3], v[86:87], v[2:3], v[82:83]
	v_exp_f32_e32 v82, v44
	v_exp_f32_e32 v83, v10
	v_lshlrev_b32_e32 v10, 16, v45
	v_and_b32_e32 v11, 0xffff0000, v45
	v_pk_fma_f32 v[4:5], v[4:5], v[80:81], v[74:75]
	v_lshlrev_b32_e32 v44, 16, v47
	v_and_b32_e32 v45, 0xffff0000, v47
	v_pk_fma_f32 v[4:5], v[68:69], v[4:5], v[10:11]
	v_lshlrev_b32_e32 v94, 16, v46
	v_and_b32_e32 v95, 0xffff0000, v46
	v_lshlrev_b32_e32 v46, 16, v55
	v_and_b32_e32 v47, 0xffff0000, v55
	v_pk_fma_f32 v[4:5], v[64:65], v[4:5], v[44:45]
	v_lshlrev_b32_e32 v96, 16, v54
	v_and_b32_e32 v97, 0xffff0000, v54
	s_waitcnt vmcnt(22)
	v_lshlrev_b32_e32 v54, 16, v59
	v_and_b32_e32 v55, 0xffff0000, v59
	v_pk_fma_f32 v[4:5], v[62:63], v[4:5], v[46:47]
	s_waitcnt vmcnt(21)
	v_lshlrev_b32_e32 v63, 16, v50
	v_pk_fma_f32 v[10:11], v[82:83], v[4:5], v[54:55]
	v_and_b32_e32 v62, 0xffff0000, v50
	v_mul_f32_e32 v4, 0x3fb8aa3b, v63
	v_lshlrev_b32_e32 v55, 16, v51
	v_exp_f32_e32 v66, v4
	v_mul_f32_e32 v4, 0x3fb8aa3b, v62
	s_waitcnt vmcnt(19)
	v_lshlrev_b32_e32 v69, 16, v48
	v_and_b32_e32 v68, 0xffff0000, v48
	v_and_b32_e32 v54, 0xffff0000, v51
	v_exp_f32_e32 v67, v4
	v_mul_f32_e32 v4, 0x3fb8aa3b, v55
	v_pk_add_f32 v[8:9], v[8:9], v[62:63]
	v_mul_f32_e32 v62, 0x3fb8aa3b, v69
	v_mul_f32_e32 v63, 0x3fb8aa3b, v68
	v_pk_fma_f32 v[2:3], v[88:89], v[2:3], v[94:95]
	v_exp_f32_e32 v50, v4
	v_mul_f32_e32 v4, 0x3fb8aa3b, v54
	s_waitcnt vmcnt(17)
	v_lshlrev_b32_e32 v75, 16, v52
	v_and_b32_e32 v74, 0xffff0000, v52
	v_exp_f32_e32 v62, v62
	v_pk_add_f32 v[8:9], v[8:9], v[68:69]
	v_exp_f32_e32 v63, v63
	v_lshlrev_b32_e32 v98, 16, v58
	v_and_b32_e32 v99, 0xffff0000, v58
	v_pk_fma_f32 v[2:3], v[90:91], v[2:3], v[96:97]
	v_lshlrev_b32_e32 v64, 16, v56
	v_and_b32_e32 v65, 0xffff0000, v56
	v_lshlrev_b32_e32 v46, 16, v57
	v_and_b32_e32 v47, 0xffff0000, v57
	v_exp_f32_e32 v51, v4
	v_lshlrev_b32_e32 v57, 16, v49
	v_and_b32_e32 v56, 0xffff0000, v49
	v_lshlrev_b32_e32 v49, 16, v53
	v_and_b32_e32 v48, 0xffff0000, v53
	s_waitcnt vmcnt(10)
	v_lshlrev_b32_e32 v52, 16, v70
	v_and_b32_e32 v53, 0xffff0000, v70
	v_lshlrev_b32_e32 v4, 16, v71
	v_and_b32_e32 v5, 0xffff0000, v71
	v_pk_add_f32 v[8:9], v[8:9], v[74:75]
	v_and_b32_e32 v70, 0xffff0000, v40
	v_lshlrev_b32_e32 v71, 16, v40
	v_pk_fma_f32 v[2:3], v[92:93], v[2:3], v[98:99]
	v_mul_f32_e32 v40, 0x3fb8aa3b, v71
	v_pk_add_f32 v[8:9], v[8:9], v[70:71]
	v_lshlrev_b32_e32 v71, 16, v38
	s_waitcnt vmcnt(8)
	v_lshlrev_b32_e32 v58, 16, v72
	v_and_b32_e32 v59, 0xffff0000, v72
	v_mul_f32_e32 v68, 0x3fb8aa3b, v75
	v_mul_f32_e32 v69, 0x3fb8aa3b, v74
	v_exp_f32_e32 v72, v40
	v_mul_f32_e32 v40, 0x3fb8aa3b, v70
	v_and_b32_e32 v70, 0xffff0000, v38
	v_mul_f32_e32 v38, 0x3fb8aa3b, v71
	v_pk_fma_f32 v[2:3], v[66:67], v[2:3], v[64:65]
	v_lshlrev_b32_e32 v64, 16, v18
	v_and_b32_e32 v65, 0xffff0000, v18
	v_exp_f32_e32 v68, v68
	v_exp_f32_e32 v69, v69
	v_exp_f32_e32 v74, v38
	v_pk_add_f32 v[8:9], v[8:9], v[70:71]
	v_mul_f32_e32 v38, 0x3fb8aa3b, v70
	v_and_b32_e32 v70, 0xffff0000, v42
	v_lshlrev_b32_e32 v71, 16, v42
	v_pk_fma_f32 v[2:3], v[62:63], v[2:3], v[64:65]
	v_lshlrev_b32_e32 v63, 16, v30
	v_pk_add_f32 v[8:9], v[8:9], v[70:71]
	v_and_b32_e32 v62, 0xffff0000, v30
	v_mul_f32_e32 v18, 0x3fb8aa3b, v63
	v_exp_f32_e32 v64, v18
	v_pk_add_f32 v[8:9], v[8:9], v[62:63]
	v_mul_f32_e32 v18, 0x3fb8aa3b, v62
	s_waitcnt vmcnt(7)
	v_lshlrev_b32_e32 v63, 16, v34
	v_lshlrev_b32_e32 v66, 16, v22
	v_and_b32_e32 v67, 0xffff0000, v22
	v_exp_f32_e32 v65, v18
	v_and_b32_e32 v62, 0xffff0000, v34
	v_mul_f32_e32 v18, 0x3fb8aa3b, v63
	v_lshlrev_b32_e32 v44, 16, v73
	v_and_b32_e32 v45, 0xffff0000, v73
	v_exp_f32_e32 v73, v40
	v_exp_f32_e32 v75, v38
	v_mul_f32_e32 v38, 0x3fb8aa3b, v71
	v_pk_fma_f32 v[2:3], v[68:69], v[2:3], v[66:67]
	v_exp_f32_e32 v66, v18
	v_pk_add_f32 v[8:9], v[8:9], v[62:63]
	v_mul_f32_e32 v18, 0x3fb8aa3b, v62
	s_waitcnt vmcnt(5)
	v_lshlrev_b32_e32 v63, 16, v32
	v_exp_f32_e32 v80, v38
	v_mul_f32_e32 v38, 0x3fb8aa3b, v70
	v_exp_f32_e32 v67, v18
	v_and_b32_e32 v62, 0xffff0000, v32
	v_mul_f32_e32 v18, 0x3fb8aa3b, v63
	v_exp_f32_e32 v81, v38
	v_exp_f32_e32 v68, v18
	v_pk_add_f32 v[8:9], v[8:9], v[62:63]
	v_mul_f32_e32 v18, 0x3fb8aa3b, v62
	s_waitcnt vmcnt(3)
	v_lshlrev_b32_e32 v63, 16, v36
	v_lshlrev_b32_e32 v70, 16, v24
	v_and_b32_e32 v71, 0xffff0000, v24
	v_exp_f32_e32 v69, v18
	v_and_b32_e32 v62, 0xffff0000, v36
	v_mul_f32_e32 v18, 0x3fb8aa3b, v63
	v_lshlrev_b32_e32 v82, 16, v28
	v_and_b32_e32 v83, 0xffff0000, v28
	v_pk_fma_f32 v[2:3], v[72:73], v[2:3], v[70:71]
	v_exp_f32_e32 v70, v18
	v_pk_add_f32 v[8:9], v[8:9], v[62:63]
	v_mul_f32_e32 v18, 0x3fb8aa3b, v62
	s_waitcnt vmcnt(1)
	v_lshlrev_b32_e32 v63, 16, v26
	v_pk_fma_f32 v[2:3], v[74:75], v[2:3], v[82:83]
	v_exp_f32_e32 v71, v18
	v_and_b32_e32 v62, 0xffff0000, v26
	v_mul_f32_e32 v18, 0x3fb8aa3b, v63
	v_exp_f32_e32 v72, v18
	v_mul_f32_e32 v18, 0x3fb8aa3b, v62
	v_pk_fma_f32 v[2:3], v[80:81], v[2:3], v[52:53]
	v_exp_f32_e32 v73, v18
	v_pk_fma_f32 v[2:3], v[64:65], v[2:3], v[58:59]
	v_lshlrev_b32_e32 v52, 16, v12
	v_and_b32_e32 v53, 0xffff0000, v12
	v_pk_fma_f32 v[2:3], v[66:67], v[2:3], v[52:53]
	v_lshlrev_b32_e32 v52, 16, v16
	v_and_b32_e32 v53, 0xffff0000, v16
	v_pk_fma_f32 v[2:3], v[68:69], v[2:3], v[52:53]
	v_lshlrev_b32_e32 v52, 16, v14
	v_and_b32_e32 v53, 0xffff0000, v14
	v_pk_fma_f32 v[2:3], v[70:71], v[2:3], v[52:53]
	s_waitcnt vmcnt(0)
	v_lshlrev_b32_e32 v52, 16, v20
	v_and_b32_e32 v53, 0xffff0000, v20
	v_mul_f32_e32 v12, 0x3fb8aa3b, v57
	v_pk_fma_f32 v[2:3], v[72:73], v[2:3], v[52:53]
	v_pk_add_f32 v[52:53], v[60:61], v[54:55]
	v_exp_f32_e32 v54, v12
	v_mul_f32_e32 v12, 0x3fb8aa3b, v56
	v_exp_f32_e32 v55, v12
	v_mul_f32_e32 v12, 0x3fb8aa3b, v49
	v_pk_add_f32 v[52:53], v[52:53], v[56:57]
	v_exp_f32_e32 v56, v12
	v_mul_f32_e32 v12, 0x3fb8aa3b, v48
	v_and_b32_e32 v40, 0xffff0000, v41
	v_lshlrev_b32_e32 v41, 16, v41
	v_exp_f32_e32 v57, v12
	v_mul_f32_e32 v12, 0x3fb8aa3b, v41
	v_pk_add_f32 v[52:53], v[52:53], v[48:49]
	v_exp_f32_e32 v48, v12
	v_mul_f32_e32 v12, 0x3fb8aa3b, v40
	v_and_b32_e32 v38, 0xffff0000, v39
	v_lshlrev_b32_e32 v39, 16, v39
	v_exp_f32_e32 v49, v12
	v_mul_f32_e32 v12, 0x3fb8aa3b, v39
	v_pk_add_f32 v[52:53], v[52:53], v[40:41]
	v_exp_f32_e32 v40, v12
	v_mul_f32_e32 v12, 0x3fb8aa3b, v38
	v_exp_f32_e32 v41, v12
	v_pk_fma_f32 v[10:11], v[50:51], v[10:11], v[46:47]
	v_lshlrev_b32_e32 v18, 16, v19
	v_and_b32_e32 v19, 0xffff0000, v19
	v_lshlrev_b32_e32 v22, 16, v23
	v_and_b32_e32 v23, 0xffff0000, v23
	v_pk_fma_f32 v[10:11], v[54:55], v[10:11], v[18:19]
	v_lshlrev_b32_e32 v24, 16, v25
	v_and_b32_e32 v25, 0xffff0000, v25
	v_pk_fma_f32 v[10:11], v[56:57], v[10:11], v[22:23]
	v_pk_add_f32 v[52:53], v[52:53], v[38:39]
	v_and_b32_e32 v38, 0xffff0000, v43
	v_lshlrev_b32_e32 v39, 16, v43
	v_lshlrev_b32_e32 v28, 16, v29
	v_and_b32_e32 v29, 0xffff0000, v29
	v_pk_fma_f32 v[10:11], v[48:49], v[10:11], v[24:25]
	v_mul_f32_e32 v12, 0x3fb8aa3b, v39
	v_pk_add_f32 v[52:53], v[52:53], v[38:39]
	v_pk_fma_f32 v[18:19], v[40:41], v[10:11], v[28:29]
	v_and_b32_e32 v10, 0xffff0000, v31
	v_lshlrev_b32_e32 v11, 16, v31
	v_exp_f32_e32 v42, v12
	v_mul_f32_e32 v12, 0x3fb8aa3b, v38
	v_pk_add_f32 v[24:25], v[52:53], v[10:11]
	v_mul_f32_e32 v10, 0x3fb8aa3b, v10
	v_exp_f32_e32 v43, v12
	v_mul_f32_e32 v12, 0x3fb8aa3b, v11
	v_exp_f32_e32 v23, v10
	v_and_b32_e32 v10, 0xffff0000, v35
	v_lshlrev_b32_e32 v11, 16, v35
	v_pk_add_f32 v[24:25], v[24:25], v[10:11]
	v_mul_f32_e32 v10, 0x3fb8aa3b, v10
	v_exp_f32_e32 v22, v12
	v_mul_f32_e32 v12, 0x3fb8aa3b, v11
	v_exp_f32_e32 v29, v10
	v_and_b32_e32 v10, 0xffff0000, v33
	v_lshlrev_b32_e32 v11, 16, v33
	v_pk_add_f32 v[24:25], v[24:25], v[10:11]
	v_mul_f32_e32 v10, 0x3fb8aa3b, v10
	v_exp_f32_e32 v28, v12
	v_mul_f32_e32 v12, 0x3fb8aa3b, v11
	v_exp_f32_e32 v31, v10
	v_and_b32_e32 v10, 0xffff0000, v37
	v_lshlrev_b32_e32 v11, 16, v37
	v_exp_f32_e32 v30, v12
	v_mul_f32_e32 v12, 0x3fb8aa3b, v11
	v_pk_add_f32 v[24:25], v[24:25], v[10:11]
	v_mul_f32_e32 v10, 0x3fb8aa3b, v10
	v_and_b32_e32 v26, 0xffff0000, v27
	v_lshlrev_b32_e32 v27, 16, v27
	v_exp_f32_e32 v32, v12
	v_exp_f32_e32 v33, v10
	v_mul_f32_e32 v10, 0x3fb8aa3b, v27
	v_mul_f32_e32 v12, 0x3fb8aa3b, v26
	v_pk_fma_f32 v[4:5], v[42:43], v[18:19], v[4:5]
	v_exp_f32_e32 v34, v10
	v_exp_f32_e32 v35, v12
	v_pk_fma_f32 v[4:5], v[22:23], v[4:5], v[44:45]
	v_lshlrev_b32_e32 v12, 16, v13
	v_and_b32_e32 v13, 0xffff0000, v13
	v_pk_fma_f32 v[4:5], v[28:29], v[4:5], v[12:13]
	v_lshlrev_b32_e32 v12, 16, v17
	v_and_b32_e32 v13, 0xffff0000, v17
	v_pk_fma_f32 v[4:5], v[30:31], v[4:5], v[12:13]
	v_lshlrev_b32_e32 v12, 16, v15
	v_and_b32_e32 v13, 0xffff0000, v15
	v_pk_fma_f32 v[4:5], v[32:33], v[4:5], v[12:13]
	v_lshlrev_b32_e32 v12, 16, v21
	v_and_b32_e32 v13, 0xffff0000, v21
	s_add_i32 s2, s2, 16
	v_pk_add_f32 v[8:9], v[8:9], v[62:63]
	v_pk_add_f32 v[10:11], v[24:25], v[26:27]
	v_pk_fma_f32 v[4:5], v[34:35], v[4:5], v[12:13]
	v_lshl_add_u64 v[6:7], v[6:7], 0, s[38:39]
	s_cmp_gt_u32 s2, 47
	s_cbranch_scc0 .LBB0_1053
	v_and_b32_e32 v6, 31, v77
	v_lshl_or_b32 v12, v78, 5, v6
	v_mul_f32_e32 v6, 0x3fb8aa3b, v9
	v_mul_f32_e32 v7, 0x3fb8aa3b, v8
	v_mul_f32_e32 v8, 0x3fb8aa3b, v11
	v_mul_f32_e32 v9, 0x3fb8aa3b, v10
	v_ashrrev_i32_e32 v13, 31, v12
	v_exp_f32_e32 v6, v6
	v_exp_f32_e32 v7, v7
	v_exp_f32_e32 v8, v8
	v_exp_f32_e32 v9, v9
	v_lshlrev_b64 v[10:11], 13, v[12:13]
	v_lshlrev_b32_e32 v12, 4, v0
	s_movk_i32 s2, 0x1ff0
	v_and_or_b32 v10, v12, s2, v10
	v_add_u32_e32 v0, s15, v0
	s_mov_b32 s2, 0xffff
	v_lshl_add_u64 v[12:13], s[0:1], 0, v[10:11]
	v_cmp_lt_i32_e32 vcc, s2, v0
	v_readlane_b32 s2, v255, 7
	global_store_dwordx4 v[12:13], v[6:9], off
	s_or_b64 s[8:9], vcc, s[8:9]
	v_add_u32_e32 v76, s2, v76
	v_lshl_add_u64 v[6:7], s[24:25], 0, v[10:11]
	global_store_dwordx4 v[6:7], v[2:5], off
	s_andn2_b64 exec, exec, s[8:9]
	s_cbranch_execnz .LBB0_1052

.LBB0_1106:
	v_ashrrev_i32_e32 v92, 14, v110
	v_bfe_u32 v97, v110, 9, 5
	v_lshlrev_b32_e32 v96, 11, v92
	s_waitcnt vmcnt(47)
	v_lshl_or_b32 v2, v97, 6, v96
	v_lshlrev_b32_e32 v0, 2, v110
	v_ashrrev_i32_e32 v3, 31, v2
	v_and_b32_e32 v109, 0x7fc, v0
	s_waitcnt vmcnt(44)
	v_mov_b64_e32 v[8:9], s[18:19]
	v_lshlrev_b32_e32 v0, 1, v109
	s_waitcnt vmcnt(1)
	v_lshlrev_b64 v[100:101], 12, v[2:3]
	v_mad_i64_i32 v[2:3], s[2:3], v2, s28, v[8:9]
	s_waitcnt vmcnt(0)
	v_lshl_add_u64 v[102:103], v[2:3], 0, v[0:1]
	s_movk_i32 s2, 0x1000
	v_lshl_add_u64 v[94:95], s[20:21], 0, v[0:1]
	v_lshl_add_u64 v[98:99], s[22:23], 0, v[0:1]
	v_add_co_u32_e32 v8, vcc, s2, v102
	v_or_b32_e32 v10, 0x1000, v100
	v_mov_b32_e32 v11, v101
	v_lshl_add_u64 v[4:5], v[94:95], 0, v[100:101]
	v_lshl_add_u64 v[6:7], v[98:99], 0, v[100:101]
	v_addc_co_u32_e32 v9, vcc, 0, v103, vcc
	v_lshl_add_u64 v[12:13], v[94:95], 0, v[10:11]
	s_movk_i32 s2, 0x7000
	global_load_dwordx2 v[2:3], v[4:5], off nt
	s_nop 0
	global_load_dwordx2 v[4:5], v[6:7], off nt
	s_nop 0
	global_load_dwordx2 v[6:7], v[8:9], off nt
	s_nop 0
	global_load_dwordx2 v[8:9], v[12:13], off nt
	v_add_co_u32_e32 v12, vcc, s2, v102
	v_or_b32_e32 v14, 0x2000, v100
	v_mov_b32_e32 v15, v101
	v_lshl_add_u64 v[10:11], v[98:99], 0, v[10:11]
	v_addc_co_u32_e32 v13, vcc, 0, v103, vcc
	v_lshl_add_u64 v[16:17], v[94:95], 0, v[14:15]
	v_lshl_add_u64 v[18:19], v[98:99], 0, v[14:15]
	s_mov_b32 s2, 0xd000
	global_load_dwordx2 v[10:11], v[10:11], off nt
	s_nop 0
	global_load_dwordx2 v[12:13], v[12:13], off nt
	s_nop 0
	global_load_dwordx2 v[14:15], v[16:17], off nt
	s_nop 0
	global_load_dwordx2 v[16:17], v[18:19], off nt
	v_add_co_u32_e32 v18, vcc, s2, v102
	s_mov_b32 s2, 0x13000
	s_nop 0
	v_addc_co_u32_e32 v19, vcc, 0, v103, vcc
	v_or_b32_e32 v20, 0x3000, v100
	v_mov_b32_e32 v21, v101
	v_add_co_u32_e32 v26, vcc, s2, v102
	v_lshl_add_u64 v[22:23], v[94:95], 0, v[20:21]
	v_lshl_add_u64 v[24:25], v[98:99], 0, v[20:21]
	v_addc_co_u32_e32 v27, vcc, 0, v103, vcc
	s_mov_b32 s2, 0x19000
	global_load_dwordx2 v[18:19], v[18:19], off nt
	s_nop 0
	global_load_dwordx2 v[20:21], v[22:23], off nt
	s_nop 0
	global_load_dwordx2 v[22:23], v[24:25], off nt
	s_nop 0
	global_load_dwordx2 v[24:25], v[26:27], off nt
	v_or_b32_e32 v26, 0x4000, v100
	v_mov_b32_e32 v27, v101
	v_add_co_u32_e32 v32, vcc, s2, v102
	v_or_b32_e32 v34, 0x5000, v100
	v_mov_b32_e32 v35, v101
	v_lshl_add_u64 v[28:29], v[94:95], 0, v[26:27]
	v_lshl_add_u64 v[30:31], v[98:99], 0, v[26:27]
	v_addc_co_u32_e32 v33, vcc, 0, v103, vcc
	v_lshl_add_u64 v[36:37], v[94:95], 0, v[34:35]
	s_mov_b32 s2, 0x1f000
	global_load_dwordx2 v[26:27], v[28:29], off nt
	s_nop 0
	global_load_dwordx2 v[28:29], v[30:31], off nt
	s_nop 0
	global_load_dwordx2 v[30:31], v[32:33], off nt
	s_nop 0
	global_load_dwordx2 v[32:33], v[36:37], off nt
	v_add_co_u32_e32 v36, vcc, s2, v102
	v_or_b32_e32 v38, 0x6000, v100
	v_mov_b32_e32 v39, v101
	v_lshl_add_u64 v[34:35], v[98:99], 0, v[34:35]
	v_addc_co_u32_e32 v37, vcc, 0, v103, vcc
	v_lshl_add_u64 v[40:41], v[94:95], 0, v[38:39]
	v_lshl_add_u64 v[42:43], v[98:99], 0, v[38:39]
	s_mov_b32 s2, 0x25000
	global_load_dwordx2 v[34:35], v[34:35], off nt
	v_or_b32_e32 v44, 0x7000, v100
	global_load_dwordx2 v[36:37], v[36:37], off nt
	s_nop 0
	global_load_dwordx2 v[38:39], v[40:41], off nt
	s_nop 0
	global_load_dwordx2 v[40:41], v[42:43], off nt
	v_add_co_u32_e32 v42, vcc, s2, v102
	v_mov_b32_e32 v45, v101
	s_nop 0
	v_addc_co_u32_e32 v43, vcc, 0, v103, vcc
	v_lshl_add_u64 v[46:47], v[94:95], 0, v[44:45]
	v_lshl_add_u64 v[48:49], v[98:99], 0, v[44:45]
	s_mov_b32 s2, 0x2b000
	global_load_dwordx2 v[42:43], v[42:43], off nt
	s_nop 0
	global_load_dwordx2 v[44:45], v[46:47], off nt
	s_nop 0
	global_load_dwordx2 v[46:47], v[48:49], off nt
	v_add_co_u32_e32 v48, vcc, s2, v102
	v_or_b32_e32 v50, 0x8000, v100
	v_mov_b32_e32 v51, v101
	v_addc_co_u32_e32 v49, vcc, 0, v103, vcc
	v_lshl_add_u64 v[52:53], v[94:95], 0, v[50:51]
	v_lshl_add_u64 v[54:55], v[98:99], 0, v[50:51]
	s_mov_b32 s2, 0x31000
	global_load_dwordx2 v[48:49], v[48:49], off nt
	s_nop 0
	global_load_dwordx2 v[50:51], v[52:53], off nt
	s_nop 0
	global_load_dwordx2 v[52:53], v[54:55], off nt
	v_add_co_u32_e32 v54, vcc, s2, v102
	v_or_b32_e32 v56, 0x9000, v100
	v_mov_b32_e32 v57, v101
	v_addc_co_u32_e32 v55, vcc, 0, v103, vcc
	v_lshl_add_u64 v[58:59], v[94:95], 0, v[56:57]
	v_lshl_add_u64 v[60:61], v[98:99], 0, v[56:57]
	s_mov_b32 s2, 0x37000
	global_load_dwordx2 v[54:55], v[54:55], off nt
	s_nop 0
	global_load_dwordx2 v[56:57], v[58:59], off nt
	s_nop 0
	global_load_dwordx2 v[58:59], v[60:61], off nt
	v_add_co_u32_e32 v60, vcc, s2, v102
	v_or_b32_e32 v62, 0xa000, v100
	v_mov_b32_e32 v63, v101
	v_addc_co_u32_e32 v61, vcc, 0, v103, vcc
	v_lshl_add_u64 v[64:65], v[94:95], 0, v[62:63]
	v_lshl_add_u64 v[66:67], v[98:99], 0, v[62:63]
	s_mov_b32 s2, 0x3d000
	global_load_dwordx2 v[60:61], v[60:61], off nt
	s_nop 0
	global_load_dwordx2 v[62:63], v[64:65], off nt
	s_nop 0
	global_load_dwordx2 v[64:65], v[66:67], off nt
	v_add_co_u32_e32 v66, vcc, s2, v102
	v_or_b32_e32 v68, 0xb000, v100
	v_mov_b32_e32 v69, v101
	v_addc_co_u32_e32 v67, vcc, 0, v103, vcc
	v_lshl_add_u64 v[70:71], v[94:95], 0, v[68:69]
	v_lshl_add_u64 v[72:73], v[98:99], 0, v[68:69]
	s_mov_b32 s2, 0x43000
	global_load_dwordx2 v[66:67], v[66:67], off nt
	s_nop 0
	global_load_dwordx2 v[68:69], v[70:71], off nt
	s_nop 0
	global_load_dwordx2 v[70:71], v[72:73], off nt
	v_add_co_u32_e32 v72, vcc, s2, v102
	v_or_b32_e32 v74, 0xc000, v100
	v_mov_b32_e32 v75, v101
	v_addc_co_u32_e32 v73, vcc, 0, v103, vcc
	v_lshl_add_u64 v[76:77], v[94:95], 0, v[74:75]
	v_lshl_add_u64 v[78:79], v[98:99], 0, v[74:75]
	s_mov_b32 s2, 0x49000
	global_load_dwordx2 v[72:73], v[72:73], off nt
	s_nop 0
	global_load_dwordx2 v[74:75], v[76:77], off nt
	s_nop 0
	global_load_dwordx2 v[76:77], v[78:79], off nt
	v_add_co_u32_e32 v78, vcc, s2, v102
	v_or_b32_e32 v80, 0xd000, v100
	v_mov_b32_e32 v81, v101
	v_addc_co_u32_e32 v79, vcc, 0, v103, vcc
	v_lshl_add_u64 v[82:83], v[94:95], 0, v[80:81]
	v_lshl_add_u64 v[84:85], v[98:99], 0, v[80:81]
	s_mov_b32 s2, 0x4f000
	global_load_dwordx2 v[78:79], v[78:79], off nt
	s_nop 0
	global_load_dwordx2 v[80:81], v[82:83], off nt
	s_nop 0
	global_load_dwordx2 v[82:83], v[84:85], off nt
	v_add_co_u32_e32 v84, vcc, s2, v102
	v_or_b32_e32 v86, 0xe000, v100
	v_mov_b32_e32 v87, v101
	v_addc_co_u32_e32 v85, vcc, 0, v103, vcc
	v_lshl_add_u64 v[88:89], v[94:95], 0, v[86:87]
	v_lshl_add_u64 v[90:91], v[98:99], 0, v[86:87]
	s_mov_b32 s2, 0x55000
	global_load_dwordx2 v[84:85], v[84:85], off nt
	s_nop 0
	global_load_dwordx2 v[86:87], v[88:89], off nt
	s_nop 0
	global_load_dwordx2 v[88:89], v[90:91], off nt
	v_add_co_u32_e32 v90, vcc, s2, v102
	v_or_b32_e32 v100, 0xf000, v100
	s_nop 0
	v_addc_co_u32_e32 v91, vcc, 0, v103, vcc
	v_lshl_add_u64 v[94:95], v[94:95], 0, v[100:101]
	v_lshl_add_u64 v[100:101], v[98:99], 0, v[100:101]
	global_load_dwordx2 v[90:91], v[90:91], off nt
	s_nop 0
	global_load_dwordx2 v[98:99], v[94:95], off nt
	s_nop 0
	global_load_dwordx2 v[100:101], v[100:101], off nt
	v_add_co_u32_e32 v94, vcc, 0x5b000, v102
	v_mov_b32_e32 v107, 0
	s_nop 0
	v_addc_co_u32_e32 v95, vcc, 0, v103, vcc
	global_load_dwordx2 v[102:103], v[94:95], off nt
	v_bfe_u32 v0, v111, 2, 9
	v_cmp_ne_u32_e32 vcc, 0, v97
	v_mov_b32_e32 v106, v107
	v_mov_b32_e32 v105, v107
	v_mov_b32_e32 v104, v107
	s_and_saveexec_b64 s[50:51], vcc
	s_cbranch_execz .LBB0_1110
	v_lshlrev_b32_e32 v92, 5, v92
	v_ashrrev_i32_e32 v93, 31, v92
	v_lshlrev_b64 v[94:95], 13, v[92:93]
	v_lshl_or_b32 v94, v0, 4, v94
	v_mov_b32_e32 v104, 0
	v_add_u32_e32 v108, -1, v97
	v_lshl_add_u64 v[94:95], s[0:1], 0, v[94:95]
	s_mov_b32 s2, 0
	s_mov_b64 s[52:53], 0
	v_lshlrev_b32_e32 v93, 2, v109
	v_mov_b32_e32 v105, v104
	v_mov_b32_e32 v106, v104
	v_mov_b32_e32 v107, v104
.LBB0_1108:
	v_add_co_u32_e32 v116, vcc, 0x100000, v94
	s_add_i32 s3, s2, 1
	s_nop 0
	v_addc_co_u32_e32 v117, vcc, 0, v95, vcc
	v_mov_b32_e32 v109, s3
	v_cmp_lt_u32_e32 vcc, s3, v97
	s_add_i32 s3, s2, 2
	v_cmp_lt_u32_e64 s[4:5], s3, v97
	v_cndmask_b32_e32 v109, v108, v109, vcc
	v_add_u32_e32 v120, v109, v92
	v_mov_b32_e32 v109, s3
	v_cndmask_b32_e64 v109, v108, v109, s[4:5]
	s_add_i32 s3, s2, 3
	v_add_u32_e32 v128, v109, v92
	v_mov_b32_e32 v109, s3
	v_cmp_lt_u32_e64 s[6:7], s3, v97
	s_add_i32 s3, s2, 4
	v_cmp_lt_u32_e64 s[8:9], s3, v97
	v_cndmask_b32_e64 v109, v108, v109, s[6:7]
	v_add_u32_e32 v136, v109, v92
	v_mov_b32_e32 v109, s3
	v_cndmask_b32_e64 v109, v108, v109, s[8:9]
	s_add_i32 s3, s2, 5
	v_add_u32_e32 v144, v109, v92
	v_mov_b32_e32 v109, s3
	v_cmp_lt_u32_e64 s[10:11], s3, v97
	s_add_i32 s3, s2, 6
	v_cmp_lt_u32_e64 s[12:13], s3, v97
	v_cndmask_b32_e64 v109, v108, v109, s[10:11]
	v_add_u32_e32 v152, v109, v92
	v_mov_b32_e32 v109, s3
	v_cndmask_b32_e64 v109, v108, v109, s[12:13]
	s_add_i32 s3, s2, 7
	v_add_u32_e32 v160, v109, v92
	v_mov_b32_e32 v109, s3
	v_cmp_lt_u32_e64 s[14:15], s3, v97
	v_ashrrev_i32_e32 v121, 31, v120
	v_ashrrev_i32_e32 v129, 31, v128
	v_cndmask_b32_e64 v109, v108, v109, s[14:15]
	v_add_u32_e32 v168, v109, v92
	v_ashrrev_i32_e32 v137, 31, v136
	v_ashrrev_i32_e32 v145, 31, v144
	v_ashrrev_i32_e32 v153, 31, v152
	v_ashrrev_i32_e32 v161, 31, v160
	v_ashrrev_i32_e32 v169, 31, v168
	v_lshlrev_b64 v[120:121], 13, v[120:121]
	v_lshlrev_b64 v[128:129], 13, v[128:129]
	v_lshlrev_b64 v[136:137], 13, v[136:137]
	v_lshlrev_b64 v[144:145], 13, v[144:145]
	v_lshlrev_b64 v[152:153], 13, v[152:153]
	v_lshlrev_b64 v[160:161], 13, v[160:161]
	v_lshlrev_b64 v[168:169], 13, v[168:169]
	v_or_b32_e32 v120, v120, v93
	v_or_b32_e32 v128, v128, v93
	v_or_b32_e32 v136, v136, v93
	v_or_b32_e32 v144, v144, v93
	v_or_b32_e32 v152, v152, v93
	v_or_b32_e32 v160, v160, v93
	v_or_b32_e32 v168, v168, v93
	v_lshl_add_u64 v[122:123], s[0:1], 0, v[120:121]
	v_lshl_add_u64 v[124:125], s[24:25], 0, v[120:121]
	v_lshl_add_u64 v[130:131], s[0:1], 0, v[128:129]
	v_lshl_add_u64 v[132:133], s[24:25], 0, v[128:129]
	v_lshl_add_u64 v[138:139], s[0:1], 0, v[136:137]
	v_lshl_add_u64 v[140:141], s[24:25], 0, v[136:137]
	v_lshl_add_u64 v[146:147], s[0:1], 0, v[144:145]
	v_lshl_add_u64 v[148:149], s[24:25], 0, v[144:145]
	v_lshl_add_u64 v[154:155], s[0:1], 0, v[152:153]
	v_lshl_add_u64 v[156:157], s[24:25], 0, v[152:153]
	v_lshl_add_u64 v[162:163], s[0:1], 0, v[160:161]
	v_lshl_add_u64 v[164:165], s[24:25], 0, v[160:161]
	v_lshl_add_u64 v[170:171], s[0:1], 0, v[168:169]
	v_lshl_add_u64 v[172:173], s[24:25], 0, v[168:169]
	global_load_dwordx4 v[112:115], v[94:95], off nt
	s_nop 0
	global_load_dwordx4 v[116:119], v[116:117], off nt
	s_nop 0
	global_load_dwordx4 v[120:123], v[122:123], off nt
	s_nop 0
	global_load_dwordx4 v[124:127], v[124:125], off nt
	s_nop 0
	global_load_dwordx4 v[128:131], v[130:131], off nt
	s_nop 0
	global_load_dwordx4 v[132:135], v[132:133], off nt
	s_nop 0
	global_load_dwordx4 v[136:139], v[138:139], off nt
	s_nop 0
	global_load_dwordx4 v[140:143], v[140:141], off nt
	s_nop 0
	global_load_dwordx4 v[144:147], v[146:147], off nt
	s_nop 0
	global_load_dwordx4 v[148:151], v[148:149], off nt
	s_nop 0
	global_load_dwordx4 v[152:155], v[154:155], off nt
	s_nop 0
	global_load_dwordx4 v[156:159], v[156:157], off nt
	s_nop 0
	global_load_dwordx4 v[160:163], v[162:163], off nt
	s_nop 0
	global_load_dwordx4 v[164:167], v[164:165], off nt
	s_nop 0
	global_load_dwordx4 v[168:171], v[170:171], off nt
	s_nop 0
	global_load_dwordx4 v[172:175], v[172:173], off nt
	s_waitcnt vmcnt(14)
	v_pk_fma_f32 v[106:107], v[106:107], v[114:115], v[118:119]
	v_pk_fma_f32 v[104:105], v[104:105], v[112:113], v[116:117]
	s_waitcnt vmcnt(12)
	v_pk_fma_f32 v[112:113], v[106:107], v[122:123], v[126:127]
	v_pk_fma_f32 v[114:115], v[104:105], v[120:121], v[124:125]
	v_cndmask_b32_e32 v107, v107, v113, vcc
	v_cndmask_b32_e32 v106, v106, v112, vcc
	v_cndmask_b32_e32 v105, v105, v115, vcc
	v_cndmask_b32_e32 v104, v104, v114, vcc
	s_waitcnt vmcnt(10)
	v_pk_fma_f32 v[112:113], v[130:131], v[106:107], v[134:135]
	v_pk_fma_f32 v[114:115], v[128:129], v[104:105], v[132:133]
	v_cndmask_b32_e64 v107, v107, v113, s[4:5]
	v_cndmask_b32_e64 v106, v106, v112, s[4:5]
	v_cndmask_b32_e64 v105, v105, v115, s[4:5]
	v_cndmask_b32_e64 v104, v104, v114, s[4:5]
	s_waitcnt vmcnt(8)
	v_pk_fma_f32 v[112:113], v[138:139], v[106:107], v[142:143]
	v_pk_fma_f32 v[114:115], v[136:137], v[104:105], v[140:141]
	v_cndmask_b32_e64 v107, v107, v113, s[6:7]
	v_cndmask_b32_e64 v106, v106, v112, s[6:7]
	v_cndmask_b32_e64 v105, v105, v115, s[6:7]
	v_cndmask_b32_e64 v104, v104, v114, s[6:7]
	s_waitcnt vmcnt(6)
	v_pk_fma_f32 v[112:113], v[146:147], v[106:107], v[150:151]
	v_pk_fma_f32 v[114:115], v[144:145], v[104:105], v[148:149]
	v_cndmask_b32_e64 v107, v107, v113, s[8:9]
	v_cndmask_b32_e64 v106, v106, v112, s[8:9]
	v_cndmask_b32_e64 v105, v105, v115, s[8:9]
	v_cndmask_b32_e64 v104, v104, v114, s[8:9]
	s_waitcnt vmcnt(4)
	v_pk_fma_f32 v[112:113], v[154:155], v[106:107], v[158:159]
	v_pk_fma_f32 v[114:115], v[152:153], v[104:105], v[156:157]
	v_cndmask_b32_e64 v107, v107, v113, s[10:11]
	v_cndmask_b32_e64 v106, v106, v112, s[10:11]
	v_cndmask_b32_e64 v105, v105, v115, s[10:11]
	v_cndmask_b32_e64 v104, v104, v114, s[10:11]
	s_waitcnt vmcnt(2)
	v_pk_fma_f32 v[112:113], v[162:163], v[106:107], v[166:167]
	v_pk_fma_f32 v[114:115], v[160:161], v[104:105], v[164:165]
	v_cndmask_b32_e64 v107, v107, v113, s[12:13]
	v_cndmask_b32_e64 v106, v106, v112, s[12:13]
	v_cndmask_b32_e64 v105, v105, v115, s[12:13]
	v_cndmask_b32_e64 v104, v104, v114, s[12:13]
	s_add_i32 s2, s2, 8
	s_waitcnt vmcnt(0)
	v_pk_fma_f32 v[112:113], v[170:171], v[106:107], v[174:175]
	v_pk_fma_f32 v[114:115], v[168:169], v[104:105], v[172:173]
	v_cmp_ge_u32_e32 vcc, s2, v97
	v_cndmask_b32_e64 v106, v106, v112, s[14:15]
	v_cndmask_b32_e64 v107, v107, v113, s[14:15]
	v_cndmask_b32_e64 v104, v104, v114, s[14:15]
	v_cndmask_b32_e64 v105, v105, v115, s[14:15]
	s_or_b64 s[52:53], vcc, s[52:53]
	v_lshl_add_u64 v[94:95], v[94:95], 0, s[38:39]
	s_andn2_b64 exec, exec, s[52:53]
	s_cbranch_execnz .LBB0_1108
	s_or_b64 exec, exec, s[52:53]
	v_readlane_b32 s15, v255, 40

.LBB0_1112:
	s_waitcnt vmcnt(47)
	v_lshlrev_b32_e32 v108, 16, v2
	v_mul_f32_e32 v108, 0x3fb8aa3b, v108
	v_exp_f32_e32 v112, v108
	v_and_b32_e32 v108, 0xffff0000, v2
	v_mul_f32_e32 v108, 0x3fb8aa3b, v108
	s_waitcnt vmcnt(44)
	v_lshlrev_b32_e32 v120, 16, v8
	v_and_b32_e32 v121, 0xffff0000, v8
	v_exp_f32_e32 v113, v108
	v_mul_f32_e32 v120, 0x3fb8aa3b, v120
	v_mul_f32_e32 v121, 0x3fb8aa3b, v121
	s_waitcnt vmcnt(41)
	v_lshlrev_b32_e32 v124, 16, v14
	v_and_b32_e32 v125, 0xffff0000, v14
	v_lshlrev_b32_e32 v108, 16, v3
	v_exp_f32_e32 v120, v120
	v_exp_f32_e32 v121, v121
	v_mul_f32_e32 v124, 0x3fb8aa3b, v124
	v_mul_f32_e32 v125, 0x3fb8aa3b, v125
	s_waitcnt vmcnt(38)
	v_lshlrev_b32_e32 v128, 16, v20
	v_and_b32_e32 v129, 0xffff0000, v20
	v_mul_f32_e32 v108, 0x3fb8aa3b, v108
	v_exp_f32_e32 v124, v124
	v_exp_f32_e32 v125, v125
	v_mul_f32_e32 v128, 0x3fb8aa3b, v128
	v_mul_f32_e32 v129, 0x3fb8aa3b, v129
	s_waitcnt vmcnt(35)
	v_lshlrev_b32_e32 v132, 16, v26
	v_and_b32_e32 v133, 0xffff0000, v26
	v_lshlrev_b32_e32 v114, 16, v4
	v_and_b32_e32 v115, 0xffff0000, v4
	v_exp_f32_e32 v116, v108
	v_and_b32_e32 v108, 0xffff0000, v3
	v_exp_f32_e32 v128, v128
	v_exp_f32_e32 v129, v129
	v_mul_f32_e32 v132, 0x3fb8aa3b, v132
	v_mul_f32_e32 v133, 0x3fb8aa3b, v133
	v_mul_f32_e32 v108, 0x3fb8aa3b, v108
	v_lshlrev_b32_e32 v134, 16, v6
	v_and_b32_e32 v135, 0xffff0000, v6
	v_exp_f32_e32 v132, v132
	v_exp_f32_e32 v133, v133
	v_pk_fma_f32 v[104:105], v[112:113], v[104:105], v[114:115]
	v_lshlrev_b32_e32 v114, 16, v10
	v_and_b32_e32 v115, 0xffff0000, v10
	v_exp_f32_e32 v117, v108
	v_lshlrev_b32_e32 v138, 16, v12
	v_and_b32_e32 v139, 0xffff0000, v12
	v_mul_f32_e32 v112, v104, v134
	v_mul_f32_e32 v113, v105, v135
	v_pk_fma_f32 v[104:105], v[120:121], v[104:105], v[114:115]
	v_lshlrev_b32_e32 v114, 16, v16
	v_and_b32_e32 v115, 0xffff0000, v16
	v_lshlrev_b32_e32 v142, 16, v18
	v_and_b32_e32 v143, 0xffff0000, v18
	v_cvt_pk_bf16_f32 v112, v112, v113
	v_mul_f32_e32 v120, v104, v138
	v_mul_f32_e32 v121, v105, v139
	v_pk_fma_f32 v[104:105], v[124:125], v[104:105], v[114:115]
	v_lshlrev_b32_e32 v114, 16, v22
	v_and_b32_e32 v115, 0xffff0000, v22
	v_lshlrev_b32_e32 v113, 16, v27
	v_lshlrev_b32_e32 v146, 16, v24
	v_and_b32_e32 v147, 0xffff0000, v24
	v_mul_f32_e32 v124, v104, v142
	v_mul_f32_e32 v125, v105, v143
	v_pk_fma_f32 v[104:105], v[128:129], v[104:105], v[114:115]
	s_waitcnt vmcnt(34)
	v_lshlrev_b32_e32 v114, 16, v28
	v_and_b32_e32 v115, 0xffff0000, v28
	v_mul_f32_e32 v113, 0x3fb8aa3b, v113
	v_lshlrev_b32_e32 v118, 16, v5
	v_and_b32_e32 v119, 0xffff0000, v5
	v_lshlrev_b32_e32 v122, 16, v9
	v_and_b32_e32 v123, 0xffff0000, v9
	v_mul_f32_e32 v128, v104, v146
	v_mul_f32_e32 v129, v105, v147
	v_pk_fma_f32 v[104:105], v[132:133], v[104:105], v[114:115]
	v_exp_f32_e32 v114, v113
	v_and_b32_e32 v113, 0xffff0000, v27
	v_lshlrev_b32_e32 v136, 16, v7
	v_and_b32_e32 v137, 0xffff0000, v7
	v_mul_f32_e32 v122, 0x3fb8aa3b, v122
	v_mul_f32_e32 v123, 0x3fb8aa3b, v123
	v_mul_f32_e32 v113, 0x3fb8aa3b, v113
	v_pk_fma_f32 v[106:107], v[116:117], v[106:107], v[118:119]
	v_lshl_add_u64 v[108:109], v[92:93], 0, v[0:1]
	v_exp_f32_e32 v122, v122
	v_exp_f32_e32 v123, v123
	v_exp_f32_e32 v115, v113
	v_mul_f32_e32 v113, v106, v136
	v_mul_f32_e32 v116, v107, v137
	s_mov_b32 s3, 0x29400000
	v_cvt_pk_bf16_f32 v113, v113, v116
	v_add_co_u32_e32 v116, vcc, s3, v108
	v_lshlrev_b32_e32 v126, 16, v15
	s_nop 0
	v_addc_co_u32_e32 v117, vcc, 0, v109, vcc
	v_and_b32_e32 v127, 0xffff0000, v15
	global_store_dwordx2 v[116:117], v[112:113], off
	v_lshlrev_b32_e32 v112, 16, v11
	v_and_b32_e32 v113, 0xffff0000, v11
	v_lshlrev_b32_e32 v140, 16, v13
	v_and_b32_e32 v141, 0xffff0000, v13
	v_mul_f32_e32 v126, 0x3fb8aa3b, v126
	v_mul_f32_e32 v127, 0x3fb8aa3b, v127
	v_pk_fma_f32 v[106:107], v[122:123], v[106:107], v[112:113]
	v_exp_f32_e32 v126, v126
	v_exp_f32_e32 v127, v127
	v_mul_f32_e32 v113, v106, v140
	v_mul_f32_e32 v116, v107, v141
	s_mov_b32 s3, 0x29402000
	v_cvt_pk_bf16_f32 v112, v120, v121
	v_cvt_pk_bf16_f32 v113, v113, v116
	v_add_co_u32_e32 v116, vcc, s3, v108
	v_lshlrev_b32_e32 v130, 16, v21
	s_nop 0
	v_addc_co_u32_e32 v117, vcc, 0, v109, vcc
	v_and_b32_e32 v131, 0xffff0000, v21
	global_store_dwordx2 v[116:117], v[112:113], off
	v_lshlrev_b32_e32 v112, 16, v17
	v_and_b32_e32 v113, 0xffff0000, v17
	v_lshlrev_b32_e32 v144, 16, v19
	v_and_b32_e32 v145, 0xffff0000, v19
	v_mul_f32_e32 v130, 0x3fb8aa3b, v130
	v_mul_f32_e32 v131, 0x3fb8aa3b, v131
	v_pk_fma_f32 v[106:107], v[126:127], v[106:107], v[112:113]
	v_exp_f32_e32 v130, v130
	v_exp_f32_e32 v131, v131
	v_mul_f32_e32 v113, v106, v144
	v_mul_f32_e32 v116, v107, v145
	s_mov_b32 s3, 0x29404000
	v_cvt_pk_bf16_f32 v112, v124, v125
	v_cvt_pk_bf16_f32 v113, v113, v116
	v_add_co_u32_e32 v116, vcc, s3, v108
	v_lshlrev_b32_e32 v148, 16, v25
	s_nop 0
	v_addc_co_u32_e32 v117, vcc, 0, v109, vcc
	global_store_dwordx2 v[116:117], v[112:113], off
	v_lshlrev_b32_e32 v112, 16, v23
	v_and_b32_e32 v113, 0xffff0000, v23
	v_and_b32_e32 v149, 0xffff0000, v25
	v_pk_fma_f32 v[106:107], v[130:131], v[106:107], v[112:113]
	s_mov_b32 s3, 0x29406000
	v_mul_f32_e32 v113, v106, v148
	v_mul_f32_e32 v116, v107, v149
	v_cvt_pk_bf16_f32 v112, v128, v129
	v_cvt_pk_bf16_f32 v113, v113, v116
	v_add_co_u32_e32 v116, vcc, s3, v108
	s_mov_b32 s3, 0x29408000
	s_nop 0
	v_addc_co_u32_e32 v117, vcc, 0, v109, vcc
	global_store_dwordx2 v[116:117], v[112:113], off
	v_lshlrev_b32_e32 v112, 16, v29
	v_and_b32_e32 v113, 0xffff0000, v29
	v_pk_fma_f32 v[106:107], v[114:115], v[106:107], v[112:113]
	s_waitcnt vmcnt(37)
	v_lshlrev_b32_e32 v112, 16, v30
	v_and_b32_e32 v113, 0xffff0000, v30
	v_mul_f32_e32 v112, v104, v112
	v_mul_f32_e32 v113, v105, v113
	v_cvt_pk_bf16_f32 v112, v112, v113
	v_lshlrev_b32_e32 v113, 16, v31
	v_and_b32_e32 v114, 0xffff0000, v31
	v_mul_f32_e32 v113, v106, v113
	v_mul_f32_e32 v114, v107, v114
	v_cvt_pk_bf16_f32 v113, v113, v114
	v_add_co_u32_e32 v114, vcc, s3, v108
	s_waitcnt vmcnt(33)
	v_lshlrev_b32_e32 v120, 16, v38
	v_addc_co_u32_e32 v115, vcc, 0, v109, vcc
	global_store_dwordx2 v[114:115], v[112:113], off
	v_lshlrev_b32_e32 v112, 16, v32
	v_and_b32_e32 v113, 0xffff0000, v32
	v_mul_f32_e32 v112, 0x3fb8aa3b, v112
	v_mul_f32_e32 v113, 0x3fb8aa3b, v113
	v_and_b32_e32 v121, 0xffff0000, v38
	v_exp_f32_e32 v112, v112
	v_exp_f32_e32 v113, v113
	v_mul_f32_e32 v120, 0x3fb8aa3b, v120
	v_mul_f32_e32 v121, 0x3fb8aa3b, v121
	s_waitcnt vmcnt(31)
	v_lshlrev_b32_e32 v124, 16, v44
	v_and_b32_e32 v125, 0xffff0000, v44
	v_exp_f32_e32 v120, v120
	v_exp_f32_e32 v121, v121
	v_mul_f32_e32 v124, 0x3fb8aa3b, v124
	v_mul_f32_e32 v125, 0x3fb8aa3b, v125
	s_waitcnt vmcnt(28)
	v_lshlrev_b32_e32 v128, 16, v50
	v_and_b32_e32 v129, 0xffff0000, v50
	v_exp_f32_e32 v124, v124
	v_exp_f32_e32 v125, v125
	v_mul_f32_e32 v128, 0x3fb8aa3b, v128
	v_mul_f32_e32 v129, 0x3fb8aa3b, v129
	s_waitcnt vmcnt(25)
	v_lshlrev_b32_e32 v132, 16, v56
	v_and_b32_e32 v133, 0xffff0000, v56
	v_lshlrev_b32_e32 v114, 16, v34
	v_and_b32_e32 v115, 0xffff0000, v34
	v_lshlrev_b32_e32 v116, 16, v33
	v_and_b32_e32 v117, 0xffff0000, v33
	v_exp_f32_e32 v128, v128
	v_exp_f32_e32 v129, v129
	v_mul_f32_e32 v132, 0x3fb8aa3b, v132
	v_mul_f32_e32 v133, 0x3fb8aa3b, v133
	v_mul_f32_e32 v116, 0x3fb8aa3b, v116
	v_mul_f32_e32 v117, 0x3fb8aa3b, v117
	v_lshlrev_b32_e32 v139, 16, v36
	v_and_b32_e32 v140, 0xffff0000, v36
	v_exp_f32_e32 v132, v132
	v_exp_f32_e32 v133, v133
	v_pk_fma_f32 v[104:105], v[112:113], v[104:105], v[114:115]
	v_lshlrev_b32_e32 v114, 16, v40
	v_and_b32_e32 v115, 0xffff0000, v40
	v_exp_f32_e32 v116, v116
	v_exp_f32_e32 v117, v117
	v_lshlrev_b32_e32 v143, 16, v42
	v_and_b32_e32 v144, 0xffff0000, v42
	v_mul_f32_e32 v112, v104, v139
	v_mul_f32_e32 v113, v105, v140
	v_pk_fma_f32 v[104:105], v[120:121], v[104:105], v[114:115]
	v_lshlrev_b32_e32 v114, 16, v46
	v_and_b32_e32 v115, 0xffff0000, v46
	v_lshlrev_b32_e32 v147, 16, v48
	v_and_b32_e32 v148, 0xffff0000, v48
	v_cvt_pk_bf16_f32 v112, v112, v113
	v_mul_f32_e32 v121, v104, v143
	v_mul_f32_e32 v140, v105, v144
	v_pk_fma_f32 v[104:105], v[124:125], v[104:105], v[114:115]
	v_lshlrev_b32_e32 v114, 16, v52
	v_and_b32_e32 v115, 0xffff0000, v52
	s_waitcnt vmcnt(22)
	v_lshlrev_b32_e32 v113, 16, v63
	v_lshlrev_b32_e32 v151, 16, v54
	v_and_b32_e32 v152, 0xffff0000, v54
	v_mul_f32_e32 v124, v104, v147
	v_mul_f32_e32 v125, v105, v148
	v_pk_fma_f32 v[104:105], v[128:129], v[104:105], v[114:115]
	v_lshlrev_b32_e32 v114, 16, v58
	v_and_b32_e32 v115, 0xffff0000, v58
	v_mul_f32_e32 v113, 0x3fb8aa3b, v113
	v_lshlrev_b32_e32 v118, 16, v35
	v_and_b32_e32 v119, 0xffff0000, v35
	v_lshlrev_b32_e32 v122, 16, v39
	v_and_b32_e32 v123, 0xffff0000, v39
	v_mul_f32_e32 v128, v104, v151
	v_mul_f32_e32 v129, v105, v152
	v_pk_fma_f32 v[104:105], v[132:133], v[104:105], v[114:115]
	v_exp_f32_e32 v114, v113
	v_and_b32_e32 v113, 0xffff0000, v63
	v_lshlrev_b32_e32 v141, 16, v37
	v_and_b32_e32 v142, 0xffff0000, v37
	v_mul_f32_e32 v122, 0x3fb8aa3b, v122
	v_mul_f32_e32 v123, 0x3fb8aa3b, v123
	v_mul_f32_e32 v113, 0x3fb8aa3b, v113
	v_pk_fma_f32 v[106:107], v[116:117], v[106:107], v[118:119]
	v_exp_f32_e32 v122, v122
	v_exp_f32_e32 v123, v123
	v_exp_f32_e32 v115, v113
	v_mul_f32_e32 v113, v106, v141
	v_mul_f32_e32 v116, v107, v142
	s_mov_b32 s3, 0x2940a000
	v_cvt_pk_bf16_f32 v113, v113, v116
	v_add_co_u32_e32 v116, vcc, s3, v108
	v_lshlrev_b32_e32 v126, 16, v45
	s_nop 0
	v_addc_co_u32_e32 v117, vcc, 0, v109, vcc
	v_and_b32_e32 v127, 0xffff0000, v45
	global_store_dwordx2 v[116:117], v[112:113], off
	v_lshlrev_b32_e32 v112, 16, v41
	v_and_b32_e32 v113, 0xffff0000, v41
	v_lshlrev_b32_e32 v145, 16, v43
	v_and_b32_e32 v146, 0xffff0000, v43
	v_mul_f32_e32 v126, 0x3fb8aa3b, v126
	v_mul_f32_e32 v127, 0x3fb8aa3b, v127
	v_pk_fma_f32 v[106:107], v[122:123], v[106:107], v[112:113]
	v_exp_f32_e32 v126, v126
	v_exp_f32_e32 v127, v127
	v_mul_f32_e32 v113, v106, v145
	v_mul_f32_e32 v116, v107, v146
	s_mov_b32 s3, 0x2940c000
	v_cvt_pk_bf16_f32 v112, v121, v140
	v_cvt_pk_bf16_f32 v113, v113, v116
	v_add_co_u32_e32 v116, vcc, s3, v108
	v_lshlrev_b32_e32 v130, 16, v51
	s_nop 0
	v_addc_co_u32_e32 v117, vcc, 0, v109, vcc
	v_and_b32_e32 v131, 0xffff0000, v51
	global_store_dwordx2 v[116:117], v[112:113], off
	v_lshlrev_b32_e32 v112, 16, v47
	v_and_b32_e32 v113, 0xffff0000, v47
	v_lshlrev_b32_e32 v149, 16, v49
	v_and_b32_e32 v150, 0xffff0000, v49
	v_mul_f32_e32 v130, 0x3fb8aa3b, v130
	v_mul_f32_e32 v131, 0x3fb8aa3b, v131
	v_pk_fma_f32 v[106:107], v[126:127], v[106:107], v[112:113]
	v_exp_f32_e32 v130, v130
	v_exp_f32_e32 v131, v131
	v_mul_f32_e32 v113, v106, v149
	v_mul_f32_e32 v116, v107, v150
	s_mov_b32 s3, 0x2940e000
	v_cvt_pk_bf16_f32 v112, v124, v125
	v_cvt_pk_bf16_f32 v113, v113, v116
	v_add_co_u32_e32 v116, vcc, s3, v108
	v_lshlrev_b32_e32 v134, 16, v57
	s_nop 0
	v_addc_co_u32_e32 v117, vcc, 0, v109, vcc
	v_and_b32_e32 v135, 0xffff0000, v57
	global_store_dwordx2 v[116:117], v[112:113], off
	v_lshlrev_b32_e32 v112, 16, v53
	v_and_b32_e32 v113, 0xffff0000, v53
	v_lshlrev_b32_e32 v153, 16, v55
	v_and_b32_e32 v154, 0xffff0000, v55
	v_mul_f32_e32 v134, 0x3fb8aa3b, v134
	v_mul_f32_e32 v135, 0x3fb8aa3b, v135
	v_pk_fma_f32 v[106:107], v[130:131], v[106:107], v[112:113]
	v_exp_f32_e32 v134, v134
	v_exp_f32_e32 v135, v135
	v_mul_f32_e32 v113, v106, v153
	v_mul_f32_e32 v116, v107, v154
	s_mov_b32 s3, 0x29410000
	v_cvt_pk_bf16_f32 v112, v128, v129
	v_cvt_pk_bf16_f32 v113, v113, v116
	v_add_co_u32_e32 v116, vcc, s3, v108
	v_lshlrev_b32_e32 v157, 16, v61
	s_nop 0
	v_addc_co_u32_e32 v117, vcc, 0, v109, vcc
	global_store_dwordx2 v[116:117], v[112:113], off
	v_lshlrev_b32_e32 v112, 16, v59
	v_and_b32_e32 v113, 0xffff0000, v59
	v_and_b32_e32 v158, 0xffff0000, v61
	v_pk_fma_f32 v[106:107], v[134:135], v[106:107], v[112:113]
	v_lshlrev_b32_e32 v155, 16, v60
	v_and_b32_e32 v156, 0xffff0000, v60
	v_mul_f32_e32 v113, v106, v157
	v_mul_f32_e32 v116, v107, v158
	s_mov_b32 s3, 0x29412000
	s_waitcnt vmcnt(23)
	v_lshlrev_b32_e32 v118, 16, v69
	v_and_b32_e32 v119, 0xffff0000, v69
	v_mul_f32_e32 v132, v104, v155
	v_mul_f32_e32 v133, v105, v156
	v_cvt_pk_bf16_f32 v112, v132, v133
	v_cvt_pk_bf16_f32 v113, v113, v116
	v_add_co_u32_e32 v116, vcc, s3, v108
	v_mul_f32_e32 v118, 0x3fb8aa3b, v118
	v_mul_f32_e32 v119, 0x3fb8aa3b, v119
	s_waitcnt vmcnt(20)
	v_lshlrev_b32_e32 v126, 16, v75
	v_and_b32_e32 v127, 0xffff0000, v75
	v_lshlrev_b32_e32 v136, 16, v62
	v_and_b32_e32 v137, 0xffff0000, v62
	v_addc_co_u32_e32 v117, vcc, 0, v109, vcc
	v_exp_f32_e32 v118, v118
	v_exp_f32_e32 v119, v119
	v_mul_f32_e32 v126, 0x3fb8aa3b, v126
	v_mul_f32_e32 v127, 0x3fb8aa3b, v127
	s_waitcnt vmcnt(17)
	v_lshlrev_b32_e32 v130, 16, v81
	v_and_b32_e32 v131, 0xffff0000, v81
	v_mul_f32_e32 v136, 0x3fb8aa3b, v136
	v_mul_f32_e32 v137, 0x3fb8aa3b, v137
	global_store_dwordx2 v[116:117], v[112:113], off
	v_lshlrev_b32_e32 v112, 16, v68
	v_and_b32_e32 v113, 0xffff0000, v68
	v_exp_f32_e32 v126, v126
	v_exp_f32_e32 v127, v127
	v_mul_f32_e32 v130, 0x3fb8aa3b, v130
	v_mul_f32_e32 v131, 0x3fb8aa3b, v131
	s_waitcnt vmcnt(15)
	v_lshlrev_b32_e32 v134, 16, v87
	v_and_b32_e32 v135, 0xffff0000, v87
	v_exp_f32_e32 v136, v136
	v_exp_f32_e32 v137, v137
	v_lshlrev_b32_e32 v120, 16, v65
	v_and_b32_e32 v121, 0xffff0000, v65
	v_mul_f32_e32 v112, 0x3fb8aa3b, v112
	v_mul_f32_e32 v113, 0x3fb8aa3b, v113
	v_exp_f32_e32 v130, v130
	v_exp_f32_e32 v131, v131
	v_mul_f32_e32 v134, 0x3fb8aa3b, v134
	v_mul_f32_e32 v135, 0x3fb8aa3b, v135
	v_lshlrev_b32_e32 v144, 16, v67
	v_and_b32_e32 v145, 0xffff0000, v67
	v_exp_f32_e32 v112, v112
	v_exp_f32_e32 v113, v113
	v_lshlrev_b32_e32 v122, 16, v71
	v_and_b32_e32 v123, 0xffff0000, v71
	v_lshlrev_b32_e32 v124, 16, v74
	v_and_b32_e32 v125, 0xffff0000, v74
	v_exp_f32_e32 v134, v134
	v_exp_f32_e32 v135, v135
	v_pk_fma_f32 v[106:107], v[114:115], v[106:107], v[120:121]
	v_lshlrev_b32_e32 v148, 16, v73
	v_and_b32_e32 v149, 0xffff0000, v73
	v_mul_f32_e32 v124, 0x3fb8aa3b, v124
	v_mul_f32_e32 v125, 0x3fb8aa3b, v125
	v_lshlrev_b32_e32 v128, 16, v80
	v_and_b32_e32 v129, 0xffff0000, v80
	v_mul_f32_e32 v120, v106, v144
	v_mul_f32_e32 v121, v107, v145
	v_pk_fma_f32 v[106:107], v[118:119], v[106:107], v[122:123]
	v_lshlrev_b32_e32 v114, 16, v77
	v_and_b32_e32 v115, 0xffff0000, v77
	v_lshlrev_b32_e32 v138, 16, v64
	v_and_b32_e32 v139, 0xffff0000, v64
	v_exp_f32_e32 v124, v124
	v_exp_f32_e32 v125, v125
	v_lshlrev_b32_e32 v152, 16, v79
	v_and_b32_e32 v153, 0xffff0000, v79
	v_mul_f32_e32 v128, 0x3fb8aa3b, v128
	v_mul_f32_e32 v129, 0x3fb8aa3b, v129
	v_lshlrev_b32_e32 v132, 16, v86
	v_and_b32_e32 v133, 0xffff0000, v86
	v_mul_f32_e32 v118, v106, v148
	v_mul_f32_e32 v119, v107, v149
	v_pk_fma_f32 v[106:107], v[126:127], v[106:107], v[114:115]
	v_lshlrev_b32_e32 v114, 16, v83
	v_and_b32_e32 v115, 0xffff0000, v83
	v_lshlrev_b32_e32 v142, 16, v66
	v_and_b32_e32 v143, 0xffff0000, v66
	v_lshlrev_b32_e32 v116, 16, v70
	v_and_b32_e32 v117, 0xffff0000, v70
	v_exp_f32_e32 v128, v128
	v_exp_f32_e32 v129, v129
	v_lshlrev_b32_e32 v156, 16, v85
	v_and_b32_e32 v157, 0xffff0000, v85
	v_mul_f32_e32 v132, 0x3fb8aa3b, v132
	v_mul_f32_e32 v133, 0x3fb8aa3b, v133
	s_waitcnt vmcnt(12)
	v_lshlrev_b32_e32 v140, 16, v98
	v_and_b32_e32 v141, 0xffff0000, v98
	v_pk_fma_f32 v[104:105], v[136:137], v[104:105], v[138:139]
	v_mul_f32_e32 v122, v106, v152
	v_mul_f32_e32 v123, v107, v153
	v_pk_fma_f32 v[106:107], v[130:131], v[106:107], v[114:115]
	v_lshlrev_b32_e32 v114, 16, v89
	v_and_b32_e32 v115, 0xffff0000, v89
	s_mov_b32 s3, 0x29414000
	v_lshlrev_b32_e32 v146, 16, v72
	v_exp_f32_e32 v132, v132
	v_exp_f32_e32 v133, v133
	v_mul_f32_e32 v140, 0x3fb8aa3b, v140
	v_mul_f32_e32 v141, 0x3fb8aa3b, v141
	v_mul_f32_e32 v136, v104, v142
	v_mul_f32_e32 v137, v105, v143
	v_pk_fma_f32 v[104:105], v[112:113], v[104:105], v[116:117]
	v_mul_f32_e32 v126, v106, v156
	v_mul_f32_e32 v127, v107, v157
	v_pk_fma_f32 v[106:107], v[134:135], v[106:107], v[114:115]
	v_add_co_u32_e32 v114, vcc, s3, v108
	v_and_b32_e32 v147, 0xffff0000, v72
	v_exp_f32_e32 v140, v140
	v_exp_f32_e32 v141, v141
	v_mul_f32_e32 v116, v104, v146
	v_lshlrev_b32_e32 v112, 16, v76
	v_and_b32_e32 v113, 0xffff0000, v76
	v_addc_co_u32_e32 v115, vcc, 0, v109, vcc
	s_mov_b32 s3, 0x29416000
	v_lshlrev_b32_e32 v150, 16, v78
	v_and_b32_e32 v151, 0xffff0000, v78
	v_cvt_pk_bf16_f32 v136, v136, v137
	v_mul_f32_e32 v117, v105, v147
	v_pk_fma_f32 v[104:105], v[124:125], v[104:105], v[112:113]
	v_lshlrev_b32_e32 v112, 16, v82
	v_and_b32_e32 v113, 0xffff0000, v82
	v_cvt_pk_bf16_f32 v137, v120, v121
	global_store_dwordx2 v[114:115], v[136:137], off
	v_cvt_pk_bf16_f32 v114, v116, v117
	v_add_co_u32_e32 v116, vcc, s3, v108
	v_lshlrev_b32_e32 v154, 16, v84
	v_and_b32_e32 v155, 0xffff0000, v84
	v_mul_f32_e32 v124, v104, v150
	v_mul_f32_e32 v125, v105, v151
	v_pk_fma_f32 v[104:105], v[128:129], v[104:105], v[112:113]
	v_lshlrev_b32_e32 v112, 16, v88
	v_and_b32_e32 v113, 0xffff0000, v88
	v_addc_co_u32_e32 v117, vcc, 0, v109, vcc
	s_mov_b32 s3, 0x29418000
	v_lshlrev_b32_e32 v158, 16, v90
	v_and_b32_e32 v159, 0xffff0000, v90
	v_mul_f32_e32 v128, v104, v154
	v_mul_f32_e32 v129, v105, v155
	v_pk_fma_f32 v[104:105], v[132:133], v[104:105], v[112:113]
	s_waitcnt vmcnt(12)
	v_lshlrev_b32_e32 v112, 16, v100
	v_and_b32_e32 v113, 0xffff0000, v100
	v_cvt_pk_bf16_f32 v115, v118, v119
	global_store_dwordx2 v[116:117], v[114:115], off
	v_add_co_u32_e32 v116, vcc, s3, v108
	v_mul_f32_e32 v132, v104, v158
	v_mul_f32_e32 v133, v105, v159
	v_pk_fma_f32 v[104:105], v[140:141], v[104:105], v[112:113]
	v_lshlrev_b32_e32 v112, 16, v99
	v_and_b32_e32 v113, 0xffff0000, v99
	v_addc_co_u32_e32 v117, vcc, 0, v109, vcc
	s_mov_b32 s3, 0x2941a000
	v_mul_f32_e32 v112, 0x3fb8aa3b, v112
	v_mul_f32_e32 v113, 0x3fb8aa3b, v113
	v_cvt_pk_bf16_f32 v114, v124, v125
	v_cvt_pk_bf16_f32 v115, v122, v123
	global_store_dwordx2 v[116:117], v[114:115], off
	v_add_co_u32_e32 v116, vcc, s3, v108
	v_exp_f32_e32 v112, v112
	v_exp_f32_e32 v113, v113
	v_addc_co_u32_e32 v117, vcc, 0, v109, vcc
	s_mov_b32 s3, 0x2941c000
	v_lshlrev_b32_e32 v160, 16, v91
	v_and_b32_e32 v161, 0xffff0000, v91
	v_cvt_pk_bf16_f32 v114, v128, v129
	v_cvt_pk_bf16_f32 v115, v126, v127
	global_store_dwordx2 v[116:117], v[114:115], off
	v_add_co_u32_e32 v116, vcc, s3, v108
	v_mul_f32_e32 v130, v106, v160
	v_mul_f32_e32 v131, v107, v161
	v_cvt_pk_bf16_f32 v114, v132, v133
	v_cvt_pk_bf16_f32 v115, v130, v131
	v_addc_co_u32_e32 v117, vcc, 0, v109, vcc
	global_store_dwordx2 v[116:117], v[114:115], off
	v_lshlrev_b32_e32 v114, 16, v101
	v_and_b32_e32 v115, 0xffff0000, v101
	v_pk_fma_f32 v[106:107], v[112:113], v[106:107], v[114:115]
	s_waitcnt vmcnt(15)
	v_lshlrev_b32_e32 v112, 16, v102
	v_and_b32_e32 v113, 0xffff0000, v102
	v_mul_f32_e32 v112, v104, v112
	v_mul_f32_e32 v113, v105, v113
	v_add_co_u32_e32 v108, vcc, 0x2941e000, v108
	s_cmp_gt_u32 s2, 47
	v_cvt_pk_bf16_f32 v112, v112, v113
	v_lshlrev_b32_e32 v113, 16, v103
	v_addc_co_u32_e32 v109, vcc, 0, v109, vcc
	s_cselect_b64 s[4:5], -1, 0
	v_mul_f32_e32 v113, v106, v113
	v_and_b32_e32 v114, 0xffff0000, v103
	s_and_b64 vcc, exec, s[4:5]
	v_mul_f32_e32 v114, v107, v114
	v_cvt_pk_bf16_f32 v113, v113, v114
	global_store_dwordx2 v[108:109], v[112:113], off
	s_cbranch_vccnz .LBB0_1111
	v_lshl_add_u64 v[98:99], v[94:95], 0, v[0:1]
	v_add_co_u32_e32 v2, vcc, 0x23410000, v98
	v_lshl_add_u64 v[102:103], v[96:97], 0, v[0:1]
	s_nop 0
	v_addc_co_u32_e32 v3, vcc, 0, v99, vcc
	v_add_co_u32_e32 v4, vcc, 0x25410000, v98
	s_nop 1
	v_addc_co_u32_e32 v5, vcc, 0, v99, vcc
	v_add_co_u32_e32 v6, vcc, 0x13461000, v102
	global_load_dwordx2 v[2:3], v[2:3], off nt
	s_nop 0
	global_load_dwordx2 v[4:5], v[4:5], off nt
	v_addc_co_u32_e32 v7, vcc, 0, v103, vcc
	v_add_co_u32_e32 v8, vcc, 0x23411000, v98
	global_load_dwordx2 v[6:7], v[6:7], off nt
	s_nop 0
	v_addc_co_u32_e32 v9, vcc, 0, v99, vcc
	v_add_co_u32_e32 v10, vcc, 0x25411000, v98
	s_nop 1
	v_addc_co_u32_e32 v11, vcc, 0, v99, vcc
	v_add_co_u32_e32 v12, vcc, 0x13467000, v102
	global_load_dwordx2 v[8:9], v[8:9], off nt
	s_nop 0
	global_load_dwordx2 v[10:11], v[10:11], off nt
	v_addc_co_u32_e32 v13, vcc, 0, v103, vcc
	v_add_co_u32_e32 v14, vcc, 0x23412000, v98
	global_load_dwordx2 v[12:13], v[12:13], off nt
	s_nop 0
	v_addc_co_u32_e32 v15, vcc, 0, v99, vcc
	v_add_co_u32_e32 v16, vcc, 0x25412000, v98
	s_nop 1
	v_addc_co_u32_e32 v17, vcc, 0, v99, vcc
	v_add_co_u32_e32 v18, vcc, 0x1346d000, v102
	global_load_dwordx2 v[14:15], v[14:15], off nt
	s_nop 0
	global_load_dwordx2 v[16:17], v[16:17], off nt
	v_addc_co_u32_e32 v19, vcc, 0, v103, vcc
	v_add_co_u32_e32 v20, vcc, 0x23413000, v98
	global_load_dwordx2 v[18:19], v[18:19], off nt
	s_nop 0
	v_addc_co_u32_e32 v21, vcc, 0, v99, vcc
	v_add_co_u32_e32 v22, vcc, 0x25413000, v98
	s_nop 1
	v_addc_co_u32_e32 v23, vcc, 0, v99, vcc
	v_add_co_u32_e32 v24, vcc, 0x13473000, v102
	global_load_dwordx2 v[20:21], v[20:21], off nt
	s_nop 0
	global_load_dwordx2 v[22:23], v[22:23], off nt
	v_addc_co_u32_e32 v25, vcc, 0, v103, vcc
	v_add_co_u32_e32 v26, vcc, 0x23414000, v98
	global_load_dwordx2 v[24:25], v[24:25], off nt
	s_nop 0
	v_addc_co_u32_e32 v27, vcc, 0, v99, vcc
	v_add_co_u32_e32 v28, vcc, 0x25414000, v98
	s_nop 1
	v_addc_co_u32_e32 v29, vcc, 0, v99, vcc
	v_add_co_u32_e32 v30, vcc, 0x13479000, v102
	global_load_dwordx2 v[26:27], v[26:27], off nt
	s_nop 0
	global_load_dwordx2 v[28:29], v[28:29], off nt
	v_addc_co_u32_e32 v31, vcc, 0, v103, vcc
	v_add_co_u32_e32 v32, vcc, 0x23415000, v98
	global_load_dwordx2 v[30:31], v[30:31], off nt
	s_nop 0
	v_addc_co_u32_e32 v33, vcc, 0, v99, vcc
	v_add_co_u32_e32 v34, vcc, 0x25415000, v98
	s_nop 1
	v_addc_co_u32_e32 v35, vcc, 0, v99, vcc
	v_add_co_u32_e32 v36, vcc, 0x1347f000, v102
	global_load_dwordx2 v[32:33], v[32:33], off nt
	s_nop 0
	global_load_dwordx2 v[34:35], v[34:35], off nt
	v_addc_co_u32_e32 v37, vcc, 0, v103, vcc
	v_add_co_u32_e32 v38, vcc, 0x23416000, v98
	global_load_dwordx2 v[36:37], v[36:37], off nt
	s_nop 0
	v_addc_co_u32_e32 v39, vcc, 0, v99, vcc
	v_add_co_u32_e32 v40, vcc, 0x25416000, v98
	s_nop 1
	v_addc_co_u32_e32 v41, vcc, 0, v99, vcc
	v_add_co_u32_e32 v42, vcc, 0x13485000, v102
	global_load_dwordx2 v[38:39], v[38:39], off nt
	s_nop 0
	global_load_dwordx2 v[40:41], v[40:41], off nt
	v_addc_co_u32_e32 v43, vcc, 0, v103, vcc
	v_add_co_u32_e32 v44, vcc, 0x23417000, v98
	global_load_dwordx2 v[42:43], v[42:43], off nt
	s_nop 0
	v_addc_co_u32_e32 v45, vcc, 0, v99, vcc
	v_add_co_u32_e32 v46, vcc, 0x25417000, v98
	s_nop 1
	v_addc_co_u32_e32 v47, vcc, 0, v99, vcc
	v_add_co_u32_e32 v48, vcc, 0x1348b000, v102
	global_load_dwordx2 v[44:45], v[44:45], off nt
	s_nop 0
	global_load_dwordx2 v[46:47], v[46:47], off nt
	v_addc_co_u32_e32 v49, vcc, 0, v103, vcc
	v_add_co_u32_e32 v50, vcc, 0x23418000, v98
	global_load_dwordx2 v[48:49], v[48:49], off nt
	s_nop 0
	v_addc_co_u32_e32 v51, vcc, 0, v99, vcc
	v_add_co_u32_e32 v52, vcc, 0x25418000, v98
	s_nop 1
	v_addc_co_u32_e32 v53, vcc, 0, v99, vcc
	v_add_co_u32_e32 v54, vcc, 0x13491000, v102
	global_load_dwordx2 v[50:51], v[50:51], off nt
	s_nop 0
	global_load_dwordx2 v[52:53], v[52:53], off nt
	v_addc_co_u32_e32 v55, vcc, 0, v103, vcc
	v_add_co_u32_e32 v56, vcc, 0x23419000, v98
	global_load_dwordx2 v[54:55], v[54:55], off nt
	s_nop 0
	v_addc_co_u32_e32 v57, vcc, 0, v99, vcc
	v_add_co_u32_e32 v58, vcc, 0x25419000, v98
	s_nop 1
	v_addc_co_u32_e32 v59, vcc, 0, v99, vcc
	v_add_co_u32_e32 v60, vcc, 0x13497000, v102
	global_load_dwordx2 v[56:57], v[56:57], off nt
	s_nop 0
	global_load_dwordx2 v[58:59], v[58:59], off nt
	v_addc_co_u32_e32 v61, vcc, 0, v103, vcc
	v_add_co_u32_e32 v62, vcc, 0x2341a000, v98
	global_load_dwordx2 v[60:61], v[60:61], off nt
	s_nop 0
	v_addc_co_u32_e32 v63, vcc, 0, v99, vcc
	v_add_co_u32_e32 v64, vcc, 0x2541a000, v98
	s_nop 1
	v_addc_co_u32_e32 v65, vcc, 0, v99, vcc
	v_add_co_u32_e32 v66, vcc, 0x1349d000, v102
	global_load_dwordx2 v[62:63], v[62:63], off nt
	s_nop 0
	global_load_dwordx2 v[64:65], v[64:65], off nt
	v_addc_co_u32_e32 v67, vcc, 0, v103, vcc
	v_add_co_u32_e32 v68, vcc, 0x2341b000, v98
	global_load_dwordx2 v[66:67], v[66:67], off nt
	s_nop 0
	v_addc_co_u32_e32 v69, vcc, 0, v99, vcc
	v_add_co_u32_e32 v70, vcc, 0x2541b000, v98
	s_nop 1
	v_addc_co_u32_e32 v71, vcc, 0, v99, vcc
	v_add_co_u32_e32 v72, vcc, 0x134a3000, v102
	global_load_dwordx2 v[68:69], v[68:69], off nt
	s_nop 0
	global_load_dwordx2 v[70:71], v[70:71], off nt
	v_addc_co_u32_e32 v73, vcc, 0, v103, vcc
	v_add_co_u32_e32 v74, vcc, 0x2341c000, v98
	global_load_dwordx2 v[72:73], v[72:73], off nt
	s_nop 0
	v_addc_co_u32_e32 v75, vcc, 0, v99, vcc
	v_add_co_u32_e32 v76, vcc, 0x2541c000, v98
	s_nop 1
	v_addc_co_u32_e32 v77, vcc, 0, v99, vcc
	v_add_co_u32_e32 v78, vcc, 0x134a9000, v102
	global_load_dwordx2 v[74:75], v[74:75], off nt
	s_nop 0
	global_load_dwordx2 v[76:77], v[76:77], off nt
	v_addc_co_u32_e32 v79, vcc, 0, v103, vcc
	v_add_co_u32_e32 v80, vcc, 0x2341d000, v98
	global_load_dwordx2 v[78:79], v[78:79], off nt
	s_nop 0
	v_addc_co_u32_e32 v81, vcc, 0, v99, vcc
	v_add_co_u32_e32 v82, vcc, 0x2541d000, v98
	s_nop 1
	v_addc_co_u32_e32 v83, vcc, 0, v99, vcc
	v_add_co_u32_e32 v84, vcc, 0x134af000, v102
	global_load_dwordx2 v[80:81], v[80:81], off nt
	s_nop 0
	global_load_dwordx2 v[82:83], v[82:83], off nt
	v_addc_co_u32_e32 v85, vcc, 0, v103, vcc
	v_add_co_u32_e32 v86, vcc, 0x2341e000, v98
	global_load_dwordx2 v[84:85], v[84:85], off nt
	s_nop 0
	v_addc_co_u32_e32 v87, vcc, 0, v99, vcc
	v_add_co_u32_e32 v88, vcc, 0x2541e000, v98
	s_nop 1
	v_addc_co_u32_e32 v89, vcc, 0, v99, vcc
	v_add_co_u32_e32 v90, vcc, 0x134b5000, v102
	global_load_dwordx2 v[86:87], v[86:87], off nt
	s_nop 0
	global_load_dwordx2 v[88:89], v[88:89], off nt
	v_addc_co_u32_e32 v91, vcc, 0, v103, vcc
	v_add_co_u32_e32 v100, vcc, 0x2341f000, v98
	global_load_dwordx2 v[90:91], v[90:91], off nt
	s_nop 0
	v_addc_co_u32_e32 v101, vcc, 0, v99, vcc
	v_add_co_u32_e32 v108, vcc, 0x2541f000, v98
	s_nop 1
	v_addc_co_u32_e32 v109, vcc, 0, v99, vcc
	v_add_co_u32_e32 v102, vcc, 0x134bb000, v102
	global_load_dwordx2 v[98:99], v[100:101], off nt
	s_nop 0
	global_load_dwordx2 v[100:101], v[108:109], off nt
	v_addc_co_u32_e32 v103, vcc, 0, v103, vcc
	global_load_dwordx2 v[102:103], v[102:103], off nt
	s_branch .LBB0_1111
